# attention: all eight V transpose-reads of a key half issued at the start of the exp block into spare registers (their LDS latency hides under the softmax VALU instead of stalling the PV MFMAs)
# speedup vs baseline: 1.0074x; 1.0025x over previous
; __device__ __forceinline__ unsigned cvt_pk_bf16(float lo, float hi) { const f32x2c_ v = {lo, hi}; const bf16x2c_ b = __builtin_convertvector(v, bf16x2c_); return __builtin_bit_cast(unsigned, b); }
; #define LAS __attribute__((address_space(3)))
; #define MFMA32(a, b, c) __builtin_amdgcn_mfma_f32_32x32x16_bf16(a, b, c, 0, 0, 0)
; __device__ __forceinline__ void attn_unit(int bh, int qb, const bf16_t* QKV, const bf16_t* KF, const float* cstab, const float* qg, bf16_t* MIX, LAS unsigned char* lds) {
;     ...
;             float ps = 0.f;
; #pragma unroll
;             for (int r = 0; r < 16; ++r) { p[r] = __builtin_amdgcn_exp2f(p[r]); ps += p[r]; }
;             lrun += ps;
;             u32x4 w0, w1;
; #pragma unroll
;             for (int k = 0; k < 4; ++k) { w0[k] = cvt_pk_bf16(p[2 * k], p[2 * k + 1]); w1[k] = cvt_pk_bf16(p[8 + 2 * k], p[8 + 2 * k + 1]); }
;             const bf16x8 pb0 = __builtin_bit_cast(bf16x8, w0), pb1 = __builtin_bit_cast(bf16x8, w1);
;             const LAS unsigned char* vp = buf + vtb + (32 * kb) * VROW;
; #pragma unroll
;             for (int db = 0; db < 2; ++db) {
;                 const v4i16_t a0 = __builtin_amdgcn_ds_read_tr16_b64_v4i16((LAS v4i16_t*)(vp + db * 64));
;                 const v4i16_t a1 = __builtin_amdgcn_ds_read_tr16_b64_v4i16((LAS v4i16_t*)(vp + db * 64 + 8 * VROW));
;                 const v4i16_t c0 = __builtin_amdgcn_ds_read_tr16_b64_v4i16((LAS v4i16_t*)(vp + db * 64 + 16 * VROW));
;                 const v4i16_t c1 = __builtin_amdgcn_ds_read_tr16_b64_v4i16((LAS v4i16_t*)(vp + db * 64 + 24 * VROW));
;                 const bf16x8 va = {a0[0], a0[1], a0[2], a0[3], a1[0], a1[1], a1[2], a1[3]}, vc = {c0[0], c0[1], c0[2], c0[3], c1[0], c1[1], c1[2], c1[3]};
;                 __builtin_amdgcn_s_setprio(1);
;                 if (db == 0) { o0 = MFMA32(va, pb0, o0); o0 = MFMA32(vc, pb1, o0); }
;                 else { o1 = MFMA32(va, pb0, o1); o1 = MFMA32(vc, pb1, o1); }
;                 __builtin_amdgcn_s_setprio(0);
;             }
.LBB0_1066:
	v_add_u32_e32 v172, v119, v115
	ds_read_b64_tr_b16 v[156:157], v172 offset:13312
	ds_read_b64_tr_b16 v[158:159], v172 offset:14848
	ds_read_b64_tr_b16 v[160:161], v172 offset:16384
	ds_read_b64_tr_b16 v[162:163], v172 offset:17920
	ds_read_b64_tr_b16 v[164:165], v172 offset:13376
	ds_read_b64_tr_b16 v[166:167], v172 offset:14912
	ds_read_b64_tr_b16 v[168:169], v172 offset:16448
	ds_read_b64_tr_b16 v[170:171], v172 offset:17984
	v_exp_f32_e32 v48, v48
	v_exp_f32_e32 v49, v49
	v_exp_f32_e32 v50, v50
	v_exp_f32_e32 v51, v51
	v_exp_f32_e32 v122, v52
	v_add_f32_e32 v121, v49, v48
	v_add_f32_e32 v121, v50, v121
	v_add_f32_e32 v121, v51, v121
	v_add_f32_e32 v52, v122, v121
	v_exp_f32_e32 v121, v53
	v_exp_f32_e32 v123, v54
	v_exp_f32_e32 v55, v55
	v_exp_f32_e32 v53, v56
	v_add_f32_e32 v52, v121, v52
	v_exp_f32_e32 v54, v57
	v_add_f32_e32 v52, v123, v52
	v_exp_f32_e32 v56, v58
	v_add_f32_e32 v52, v55, v52
	v_exp_f32_e32 v57, v59
	v_add_f32_e32 v52, v53, v52
	v_exp_f32_e32 v58, v60
	v_add_f32_e32 v52, v54, v52
	v_exp_f32_e32 v59, v61
	v_add_f32_e32 v52, v56, v52
	v_exp_f32_e32 v60, v62
	v_add_f32_e32 v52, v57, v52
	v_exp_f32_e32 v61, v63
	v_add_f32_e32 v52, v58, v52
	v_add_f32_e32 v52, v59, v52
	v_add_f32_e32 v52, v60, v52
	v_cvt_pk_bf16_f32 v48, v48, v49
	v_cvt_pk_bf16_f32 v49, v50, v51
	v_cvt_pk_bf16_f32 v50, v122, v121
	v_add_f32_e32 v124, v61, v52
	v_cvt_pk_bf16_f32 v52, v53, v54
	v_cvt_pk_bf16_f32 v53, v56, v57
	v_cvt_pk_bf16_f32 v54, v58, v59
	v_cvt_pk_bf16_f32 v51, v123, v55
	v_cvt_pk_bf16_f32 v55, v60, v61
	s_setprio 1
	s_waitcnt lgkmcnt(6)
	v_mfma_f32_32x32x16_bf16 v[0:15], v[156:159], v[48:51], v[0:15]
	s_waitcnt lgkmcnt(4)
	v_mfma_f32_32x32x16_bf16 v[0:15], v[160:163], v[52:55], v[0:15]
	s_setprio 0
	s_setprio 1
	s_waitcnt lgkmcnt(2)
	v_mfma_f32_32x32x16_bf16 v[16:31], v[164:167], v[48:51], v[16:31]
	s_waitcnt lgkmcnt(0)
	v_mfma_f32_32x32x16_bf16 v[16:31], v[168:171], v[52:55], v[16:31]
	s_setprio 0
	v_add_f32_e32 v107, v107, v124
	s_add_i32 s44, s43, 0x60
	s_cmp_gt_i32 s44, s2
	s_cbranch_scc0 .LBB0_1069

; __device__ __forceinline__ unsigned cvt_pk_bf16(float lo, float hi) { const f32x2c_ v = {lo, hi}; const bf16x2c_ b = __builtin_convertvector(v, bf16x2c_); return __builtin_bit_cast(unsigned, b); }
; #define LAS __attribute__((address_space(3)))
; #define MFMA32(a, b, c) __builtin_amdgcn_mfma_f32_32x32x16_bf16(a, b, c, 0, 0, 0)
; __device__ __forceinline__ void attn_unit(int bh, int qb, const bf16_t* QKV, const bf16_t* KF, const float* cstab, const float* qg, bf16_t* MIX, LAS unsigned char* lds) {
;     ...
;             float ps = 0.f;
; #pragma unroll
;             for (int r = 0; r < 16; ++r) { p[r] = __builtin_amdgcn_exp2f(p[r]); ps += p[r]; }
;             lrun += ps;
;             u32x4 w0, w1;
; #pragma unroll
;             for (int k = 0; k < 4; ++k) { w0[k] = cvt_pk_bf16(p[2 * k], p[2 * k + 1]); w1[k] = cvt_pk_bf16(p[8 + 2 * k], p[8 + 2 * k + 1]); }
;             const bf16x8 pb0 = __builtin_bit_cast(bf16x8, w0), pb1 = __builtin_bit_cast(bf16x8, w1);
;             const LAS unsigned char* vp = buf + vtb + (32 * kb) * VROW;
; #pragma unroll
;             for (int db = 0; db < 2; ++db) {
;                 const v4i16_t a0 = __builtin_amdgcn_ds_read_tr16_b64_v4i16((LAS v4i16_t*)(vp + db * 64));
;                 const v4i16_t a1 = __builtin_amdgcn_ds_read_tr16_b64_v4i16((LAS v4i16_t*)(vp + db * 64 + 8 * VROW));
;                 const v4i16_t c0 = __builtin_amdgcn_ds_read_tr16_b64_v4i16((LAS v4i16_t*)(vp + db * 64 + 16 * VROW));
;                 const v4i16_t c1 = __builtin_amdgcn_ds_read_tr16_b64_v4i16((LAS v4i16_t*)(vp + db * 64 + 24 * VROW));
;                 const bf16x8 va = {a0[0], a0[1], a0[2], a0[3], a1[0], a1[1], a1[2], a1[3]}, vc = {c0[0], c0[1], c0[2], c0[3], c1[0], c1[1], c1[2], c1[3]};
;                 __builtin_amdgcn_s_setprio(1);
;                 if (db == 0) { o0 = MFMA32(va, pb0, o0); o0 = MFMA32(vc, pb1, o0); }
;                 else { o1 = MFMA32(va, pb0, o1); o1 = MFMA32(vc, pb1, o1); }
;                 __builtin_amdgcn_s_setprio(0);
;             }
.LBB0_1073:
	v_add_u32_e32 v172, v119, v115
	ds_read_b64_tr_b16 v[156:157], v172 offset:19456
	ds_read_b64_tr_b16 v[158:159], v172 offset:20992
	ds_read_b64_tr_b16 v[160:161], v172 offset:22528
	ds_read_b64_tr_b16 v[162:163], v172 offset:24064
	ds_read_b64_tr_b16 v[164:165], v172 offset:19520
	ds_read_b64_tr_b16 v[166:167], v172 offset:21056
	ds_read_b64_tr_b16 v[168:169], v172 offset:22592
	ds_read_b64_tr_b16 v[170:171], v172 offset:24128
	v_exp_f32_e32 v48, v48
	v_exp_f32_e32 v49, v49
	v_exp_f32_e32 v50, v50
	v_exp_f32_e32 v51, v51
	v_exp_f32_e32 v121, v52
	v_add_f32_e32 v120, v49, v48
	v_add_f32_e32 v120, v50, v120
	v_add_f32_e32 v120, v51, v120
	v_add_f32_e32 v52, v121, v120
	v_exp_f32_e32 v120, v53
	v_exp_f32_e32 v122, v54
	v_exp_f32_e32 v55, v55
	v_exp_f32_e32 v53, v56
	v_add_f32_e32 v52, v120, v52
	v_exp_f32_e32 v54, v57
	v_add_f32_e32 v52, v122, v52
	v_exp_f32_e32 v56, v58
	v_add_f32_e32 v52, v55, v52
	v_exp_f32_e32 v57, v59
	v_add_f32_e32 v52, v53, v52
	v_exp_f32_e32 v58, v60
	v_add_f32_e32 v52, v54, v52
	v_exp_f32_e32 v59, v61
	v_add_f32_e32 v52, v56, v52
	v_exp_f32_e32 v60, v62
	v_add_f32_e32 v52, v57, v52
	v_exp_f32_e32 v61, v63
	v_add_f32_e32 v52, v58, v52
	v_add_f32_e32 v52, v59, v52
	v_add_f32_e32 v52, v60, v52
	v_add_f32_e32 v123, v61, v52
	v_cvt_pk_bf16_f32 v48, v48, v49
	v_cvt_pk_bf16_f32 v52, v53, v54
	v_cvt_pk_bf16_f32 v49, v50, v51
	v_cvt_pk_bf16_f32 v53, v56, v57
	v_cvt_pk_bf16_f32 v54, v58, v59
	v_cvt_pk_bf16_f32 v51, v122, v55
	v_cvt_pk_bf16_f32 v55, v60, v61
	v_cvt_pk_bf16_f32 v50, v121, v120
	s_setprio 1
	s_waitcnt lgkmcnt(6)
	v_mfma_f32_32x32x16_bf16 v[0:15], v[156:159], v[48:51], v[0:15]
	s_waitcnt lgkmcnt(4)
	v_mfma_f32_32x32x16_bf16 v[0:15], v[160:163], v[52:55], v[0:15]
	s_setprio 0
	s_setprio 1
	s_waitcnt lgkmcnt(2)
	v_mfma_f32_32x32x16_bf16 v[16:31], v[164:167], v[48:51], v[16:31]
	s_waitcnt lgkmcnt(0)
	v_mfma_f32_32x32x16_bf16 v[16:31], v[168:171], v[52:55], v[16:31]
	s_setprio 0
	v_add_f32_e32 v107, v107, v123
	s_andn2_b64 vcc, exec, s[4:5]
	s_cbranch_vccnz .LBB0_1077

; __device__ __forceinline__ unsigned cvt_pk_bf16(float lo, float hi) { const f32x2c_ v = {lo, hi}; const bf16x2c_ b = __builtin_convertvector(v, bf16x2c_); return __builtin_bit_cast(unsigned, b); }
; #define LAS __attribute__((address_space(3)))
; #define MFMA32(a, b, c) __builtin_amdgcn_mfma_f32_32x32x16_bf16(a, b, c, 0, 0, 0)
; __device__ __forceinline__ void attn_unit(int bh, int qb, const bf16_t* QKV, const bf16_t* KF, const float* cstab, const float* qg, bf16_t* MIX, LAS unsigned char* lds) {
;     ...
;             float ps = 0.f;
; #pragma unroll
;             for (int r = 0; r < 16; ++r) { p[r] = __builtin_amdgcn_exp2f(p[r]); ps += p[r]; }
;             lrun += ps;
;             u32x4 w0, w1;
; #pragma unroll
;             for (int k = 0; k < 4; ++k) { w0[k] = cvt_pk_bf16(p[2 * k], p[2 * k + 1]); w1[k] = cvt_pk_bf16(p[8 + 2 * k], p[8 + 2 * k + 1]); }
;             const bf16x8 pb0 = __builtin_bit_cast(bf16x8, w0), pb1 = __builtin_bit_cast(bf16x8, w1);
;             const LAS unsigned char* vp = buf + vtb + (32 * kb) * VROW;
; #pragma unroll
;             for (int db = 0; db < 2; ++db) {
;                 const v4i16_t a0 = __builtin_amdgcn_ds_read_tr16_b64_v4i16((LAS v4i16_t*)(vp + db * 64));
;                 const v4i16_t a1 = __builtin_amdgcn_ds_read_tr16_b64_v4i16((LAS v4i16_t*)(vp + db * 64 + 8 * VROW));
;                 const v4i16_t c0 = __builtin_amdgcn_ds_read_tr16_b64_v4i16((LAS v4i16_t*)(vp + db * 64 + 16 * VROW));
;                 const v4i16_t c1 = __builtin_amdgcn_ds_read_tr16_b64_v4i16((LAS v4i16_t*)(vp + db * 64 + 24 * VROW));
;                 const bf16x8 va = {a0[0], a0[1], a0[2], a0[3], a1[0], a1[1], a1[2], a1[3]}, vc = {c0[0], c0[1], c0[2], c0[3], c1[0], c1[1], c1[2], c1[3]};
;                 __builtin_amdgcn_s_setprio(1);
;                 if (db == 0) { o0 = MFMA32(va, pb0, o0); o0 = MFMA32(vc, pb1, o0); }
;                 else { o1 = MFMA32(va, pb0, o1); o1 = MFMA32(vc, pb1, o1); }
;                 __builtin_amdgcn_s_setprio(0);
;             }
.LBB0_1107:
	v_add_u32_e32 v172, v119, v115
	ds_read_b64_tr_b16 v[156:157], v172 offset:13312
	ds_read_b64_tr_b16 v[158:159], v172 offset:14848
	ds_read_b64_tr_b16 v[160:161], v172 offset:16384
	ds_read_b64_tr_b16 v[162:163], v172 offset:17920
	ds_read_b64_tr_b16 v[164:165], v172 offset:13376
	ds_read_b64_tr_b16 v[166:167], v172 offset:14912
	ds_read_b64_tr_b16 v[168:169], v172 offset:16448
	ds_read_b64_tr_b16 v[170:171], v172 offset:17984
	v_exp_f32_e32 v48, v48
	v_exp_f32_e32 v49, v49
	v_exp_f32_e32 v50, v50
	v_exp_f32_e32 v51, v51
	v_exp_f32_e32 v122, v52
	v_add_f32_e32 v121, v49, v48
	v_add_f32_e32 v121, v50, v121
	v_add_f32_e32 v121, v51, v121
	v_add_f32_e32 v52, v122, v121
	v_exp_f32_e32 v121, v53
	v_exp_f32_e32 v123, v54
	v_exp_f32_e32 v55, v55
	v_exp_f32_e32 v53, v56
	v_add_f32_e32 v52, v121, v52
	v_exp_f32_e32 v54, v57
	v_add_f32_e32 v52, v123, v52
	v_exp_f32_e32 v56, v58
	v_add_f32_e32 v52, v55, v52
	v_exp_f32_e32 v57, v59
	v_add_f32_e32 v52, v53, v52
	v_exp_f32_e32 v58, v60
	v_add_f32_e32 v52, v54, v52
	v_exp_f32_e32 v59, v61
	v_add_f32_e32 v52, v56, v52
	v_exp_f32_e32 v60, v62
	v_add_f32_e32 v52, v57, v52
	v_exp_f32_e32 v61, v63
	v_add_f32_e32 v52, v58, v52
	v_add_f32_e32 v52, v59, v52
	v_add_f32_e32 v52, v60, v52
	v_cvt_pk_bf16_f32 v48, v48, v49
	v_cvt_pk_bf16_f32 v49, v50, v51
	v_cvt_pk_bf16_f32 v50, v122, v121
	v_add_f32_e32 v124, v61, v52
	v_cvt_pk_bf16_f32 v52, v53, v54
	v_cvt_pk_bf16_f32 v53, v56, v57
	v_cvt_pk_bf16_f32 v54, v58, v59
	v_cvt_pk_bf16_f32 v51, v123, v55
	v_cvt_pk_bf16_f32 v55, v60, v61
	s_setprio 1
	s_waitcnt lgkmcnt(6)
	v_mfma_f32_32x32x16_bf16 v[0:15], v[156:159], v[48:51], v[0:15]
	s_waitcnt lgkmcnt(4)
	v_mfma_f32_32x32x16_bf16 v[0:15], v[160:163], v[52:55], v[0:15]
	s_setprio 0
	s_setprio 1
	s_waitcnt lgkmcnt(2)
	v_mfma_f32_32x32x16_bf16 v[16:31], v[164:167], v[48:51], v[16:31]
	s_waitcnt lgkmcnt(0)
	v_mfma_f32_32x32x16_bf16 v[16:31], v[168:171], v[52:55], v[16:31]
	s_setprio 0
	v_add_f32_e32 v107, v107, v124
	s_add_i32 s30, s29, 0x60
	s_cmp_gt_i32 s30, s18
	s_cbranch_scc0 .LBB0_1110
